# P4 NSA/DSA loops: the 62 plain v_pk_add_f32 between MFMAs split into two v_add_f32 each (packed fp32 issue cost, doc 7.5); bit-identical
# speedup vs baseline: 1.0003x; 1.0003x over previous
; #define LAS __attribute__((address_space(3)))
; #define MFMA32(a, b, c) __builtin_amdgcn_mfma_f32_32x32x16_bf16((a), (b), (c), 0, 0, 0)
; DI float fexp2(float x) { return __builtin_amdgcn_exp2f(x); }
; DI void flash_pv2(FState& sa, FState& sb, f32x16& a0, f32x16& a1, bool rona, f32x16& b0, f32x16& b1, bool ronb, const LAS unsigned char* va, const LAS unsigned char* vbb, int lane) {
;     ...
;     const float cla = rona ? SM_C : 0.0f, bla = rona ? ((sa.m == NINF) ? 0.0f : -sa.m * SM_C) : NINF;
;     const float clb = ronb ? SM_C : 0.0f, blb = ronb ? ((sb.m == NINF) ? 0.0f : -sb.m * SM_C) : NINF;
;     float suma = 0.f, sumb = 0.f;
; #pragma unroll
;     for (int r = 0; r < 16; ++r) {
;         a0[r] = fexp2(__builtin_fmaf(a0[r], cla, bla)); b0[r] = fexp2(__builtin_fmaf(b0[r], clb, blb));
;         a1[r] = fexp2(__builtin_fmaf(a1[r], cla, bla)); b1[r] = fexp2(__builtin_fmaf(b1[r], clb, blb));
;         suma += a0[r] + a1[r]; sumb += b0[r] + b1[r];
;     }
;     sa.l += suma; sb.l += sumb;
;     const int h = lane >> 5;
;     const int vx = (((lane & 15) >> 3) & 1) * 64;
;     const int voff = (4 * h + ((lane & 15) >> 2)) * 128 + ((lane >> 4) & 1) * 32 + (lane & 3) * 8;
; #pragma unroll
;     for (int sub = 0; sub < 2; ++sub)
; #pragma unroll
;         for (int s2 = 0; s2 < 2; ++s2) {
;             const bf16x8 pfa = pack8h(sub ? a1 : a0, s2), pfb = pack8h(sub ? b1 : b0, s2);
;             const LAS unsigned char* qa = va + voff + (32 * sub + 16 * s2) * 128; const LAS unsigned char* qb = vbb + voff + (32 * sub + 16 * s2) * 128;
;             { const s16x4 lo = vtr(qa + vx), hi = vtr(qa + 1024 + vx); const bf16x8 vf = {lo[0], lo[1], lo[2], lo[3], hi[0], hi[1], hi[2], hi[3]}; sa.o0 = MFMA32(vf, pfa, sa.o0); }
;             { const s16x4 lo = vtr(qb + vx), hi = vtr(qb + 1024 + vx); const bf16x8 vf = {lo[0], lo[1], lo[2], lo[3], hi[0], hi[1], hi[2], hi[3]}; sb.o0 = MFMA32(vf, pfb, sb.o0); }
;             { const s16x4 lo = vtr(qa + (64 - vx)), hi = vtr(qa + 1024 + (64 - vx)); const bf16x8 vf = {lo[0], lo[1], lo[2], lo[3], hi[0], hi[1], hi[2], hi[3]}; sa.o1 = MFMA32(vf, pfa, sa.o1); }
;             { const s16x4 lo = vtr(qb + (64 - vx)), hi = vtr(qb + 1024 + (64 - vx)); const bf16x8 vf = {lo[0], lo[1], lo[2], lo[3], hi[0], hi[1], hi[2], hi[3]}; sb.o1 = MFMA32(vf, pfb, sb.o1); }
.LBB0_733:
	v_mul_f32_e32 v182, 0xbe38aa3b, v180
	v_cmp_neq_f32_e32 vcc, s62, v180
	s_add_i32 s51, s51, 2
	s_add_i32 s16, s16, 0x8000
	v_cndmask_b32_e32 v221, 0, v182, vcc
	v_fmamk_f32 v68, v68, 0x3e38aa3b, v221
	v_fmamk_f32 v100, v100, 0x3e38aa3b, v221
	v_exp_f32_e32 v184, v68
	v_fma_f32 v68, s4, v84, v187
	v_exp_f32_e32 v182, v100
	v_fma_f32 v100, s4, v116, v187
	v_exp_f32_e32 v183, v68
	v_fmamk_f32 v68, v101, 0x3e38aa3b, v221
	v_exp_f32_e32 v185, v100
	v_exp_f32_e32 v100, v68
	v_fma_f32 v68, s4, v117, v187
	v_exp_f32_e32 v189, v68
	v_fmamk_f32 v68, v69, 0x3e38aa3b, v221
	v_fma_f32 v69, s4, v118, v187
	v_fmamk_f32 v74, v74, 0x3e38aa3b, v221
	v_exp_f32_e32 v117, v69
	v_fmamk_f32 v69, v70, 0x3e38aa3b, v221
	v_exp_f32_e32 v196, v74
	v_fma_f32 v74, s4, v90, v187
	v_exp_f32_e32 v188, v68
	v_fma_f32 v68, s4, v85, v187
	v_exp_f32_e32 v116, v69
	v_fma_f32 v69, s4, v86, v187
	v_fma_f32 v86, s4, v121, v187
	v_exp_f32_e32 v121, v74
	v_fmamk_f32 v74, v107, 0x3e38aa3b, v221
	v_exp_f32_e32 v101, v68
	v_fmamk_f32 v68, v102, 0x3e38aa3b, v221
	v_fmamk_f32 v72, v72, 0x3e38aa3b, v221
	v_fmamk_f32 v102, v106, 0x3e38aa3b, v221
	v_exp_f32_e32 v90, v74
	v_fma_f32 v74, s4, v123, v187
	v_fmamk_f32 v77, v77, 0x3e38aa3b, v221
	v_fmamk_f32 v70, v103, 0x3e38aa3b, v221
	v_fma_f32 v85, s4, v120, v187
	v_exp_f32_e32 v190, v72
	v_fma_f32 v72, s4, v88, v187
	v_exp_f32_e32 v120, v102
	v_fma_f32 v102, s4, v122, v187
	v_exp_f32_e32 v103, v74
	v_fmamk_f32 v74, v75, 0x3e38aa3b, v221
	v_fma_f32 v75, s4, v124, v187
	v_exp_f32_e32 v106, v77
	v_fma_f32 v77, s4, v93, v187
	v_fma_f32 v93, s4, v126, v187
	v_fmamk_f32 v71, v71, 0x3e38aa3b, v221
	v_exp_f32_e32 v191, v85
	v_exp_f32_e32 v85, v72
	v_fmamk_f32 v72, v105, 0x3e38aa3b, v221
	v_exp_f32_e32 v197, v102
	v_exp_f32_e32 v102, v74
	v_fma_f32 v74, s4, v91, v187
	v_exp_f32_e32 v105, v75
	v_fmamk_f32 v75, v76, 0x3e38aa3b, v221
	v_fmamk_f32 v76, v109, 0x3e38aa3b, v221
	v_exp_f32_e32 v109, v93
	v_fmamk_f32 v78, v78, 0x3e38aa3b, v221
	v_fma_f32 v93, s4, v127, v187
	v_exp_f32_e32 v68, v68
	v_exp_f32_e32 v69, v69
	v_fma_f32 v84, s4, v119, v187
	v_exp_f32_e32 v118, v71
	v_fma_f32 v71, s4, v87, v187
	v_exp_f32_e32 v91, v74
	v_fmamk_f32 v74, v108, 0x3e38aa3b, v221
	v_exp_f32_e32 v108, v78
	v_fmamk_f32 v78, v111, 0x3e38aa3b, v221
	v_exp_f32_e32 v111, v93
	v_fmamk_f32 v93, v112, 0x3e38aa3b, v221
	v_exp_f32_e32 v70, v70
	v_exp_f32_e32 v119, v84
	v_exp_f32_e32 v71, v71
	v_fmamk_f32 v84, v104, 0x3e38aa3b, v221
	v_fmamk_f32 v73, v73, 0x3e38aa3b, v221
	v_exp_f32_e32 v112, v93
	v_add_u32_e32 v93, s73, v219
	v_exp_f32_e32 v84, v84
	v_exp_f32_e32 v193, v86
	v_exp_f32_e32 v192, v73
	v_fma_f32 v73, s4, v89, v187
	v_add_f32_e32 v86, v182, v184
	v_add_f32_e32 v87, v183, v185
	v_cvt_pk_bf16_f32 v122, v182, v100
	v_add_u32_e32 v182, v93, v202
	v_exp_f32_e32 v72, v72
	v_exp_f32_e32 v73, v73
	v_pk_add_f32 v[86:87], v[86:87], 0 op_sel_hi:[1,0]
	v_add_f32_e32 v88, v100, v188
	v_add_f32_e32 v89, v101, v189
	s_waitcnt vmcnt(0)
	ds_read_b64_tr_b16 v[222:223], v182 offset:8192
	ds_read_b64_tr_b16 v[224:225], v182 offset:9216
	v_add_f32_e32 v86, v88, v86
	v_add_f32_e32 v87, v89, v87
	v_add_f32_e32 v88, v68, v116
	v_add_f32_e32 v89, v69, v117
	v_cvt_pk_bf16_f32 v123, v68, v70
	v_add_f32_e32 v86, v88, v86
	v_add_f32_e32 v87, v89, v87
	v_add_f32_e32 v88, v70, v118
	v_add_f32_e32 v89, v71, v119
	ds_read_b64_tr_b16 v[230:231], v182 offset:24576
	ds_read_b64_tr_b16 v[232:233], v182 offset:25600
	ds_read_b64_tr_b16 v[234:235], v182 offset:10240
	ds_read_b64_tr_b16 v[236:237], v182 offset:11264
	v_fma_f32 v68, s4, v128, v187
	v_add_f32_e32 v86, v88, v86
	v_add_f32_e32 v87, v89, v87
	v_add_f32_e32 v88, v84, v190
	v_add_f32_e32 v89, v85, v191
	v_exp_f32_e32 v247, v68
	v_fmamk_f32 v68, v113, 0x3e38aa3b, v221
	v_add_f32_e32 v86, v88, v86
	v_add_f32_e32 v87, v89, v87
	v_add_f32_e32 v88, v72, v192
	v_add_f32_e32 v89, v73, v193
	v_exp_f32_e32 v104, v75
	v_fma_f32 v75, s4, v92, v187
	v_fma_f32 v92, s4, v125, v187
	v_cvt_pk_bf16_f32 v124, v84, v72
	v_cvt_pk_bf16_f32 v125, v120, v90
	v_cvt_pk_bf16_f32 v226, v185, v189
	v_cvt_pk_bf16_f32 v227, v117, v119
	v_cvt_pk_bf16_f32 v228, v191, v193
	v_cvt_pk_bf16_f32 v229, v197, v103
	v_add_u32_e32 v72, v93, v220
	v_exp_f32_e32 v248, v68
	v_fma_f32 v68, s4, v129, v187
	s_waitcnt lgkmcnt(4)
	v_mfma_f32_32x32x16_bf16 v[52:67], v[222:225], v[122:125], v[52:67]
	ds_read_b64_tr_b16 v[222:223], v72 offset:8256
	ds_read_b64_tr_b16 v[224:225], v72 offset:9280
	ds_read_b64_tr_b16 v[238:239], v182 offset:26624
	ds_read_b64_tr_b16 v[240:241], v182 offset:27648
	v_exp_f32_e32 v251, v68
	v_fmamk_f32 v68, v114, 0x3e38aa3b, v221
	v_exp_f32_e32 v84, v68
	v_fma_f32 v68, s4, v130, v187
	v_exp_f32_e32 v107, v92
	v_fmamk_f32 v92, v110, 0x3e38aa3b, v221
	s_waitcnt lgkmcnt(6)
	v_mfma_f32_32x32x16_bf16 v[36:51], v[230:233], v[226:229], v[36:51]
	ds_read_b64_tr_b16 v[230:231], v72 offset:24640
	ds_read_b64_tr_b16 v[232:233], v72 offset:25664
	ds_read_b64_tr_b16 v[242:243], v72 offset:10304
	ds_read_b64_tr_b16 v[244:245], v72 offset:11328
	v_fmamk_f32 v70, v115, 0x3e38aa3b, v221
	v_exp_f32_e32 v189, v68
	v_fma_f32 v68, s4, v131, v187
	v_exp_f32_e32 v74, v74
	v_exp_f32_e32 v76, v76
	v_exp_f32_e32 v92, v92
	v_exp_f32_e32 v78, v78
	s_waitcnt lgkmcnt(6)
; #define LAS __attribute__((address_space(3)))
; #define MFMA32(a, b, c) __builtin_amdgcn_mfma_f32_32x32x16_bf16((a), (b), (c), 0, 0, 0)
; DI float fexp2(float x) { return __builtin_amdgcn_exp2f(x); }
; DI s16x4 vtr(const LAS unsigned char* p) { return __builtin_bit_cast(s16x4, __builtin_amdgcn_ds_read_tr16_b64_v4i16((LAS v4i16_t*)p)); }
; DI void flash_pv2(FState& sa, FState& sb, f32x16& a0, f32x16& a1, bool rona, f32x16& b0, f32x16& b1, bool ronb, const LAS unsigned char* va, const LAS unsigned char* vbb, int lane) {
;     ...
;     for (int r = 0; r < 16; ++r) {
;         a0[r] = fexp2(__builtin_fmaf(a0[r], cla, bla)); b0[r] = fexp2(__builtin_fmaf(b0[r], clb, blb));
;         a1[r] = fexp2(__builtin_fmaf(a1[r], cla, bla)); b1[r] = fexp2(__builtin_fmaf(b1[r], clb, blb));
;         suma += a0[r] + a1[r]; sumb += b0[r] + b1[r];
;     }
;     sa.l += suma; sb.l += sumb;
;     const int h = lane >> 5;
;     const int vx = (((lane & 15) >> 3) & 1) * 64;
;     const int voff = (4 * h + ((lane & 15) >> 2)) * 128 + ((lane >> 4) & 1) * 32 + (lane & 3) * 8;
; #pragma unroll
;     for (int sub = 0; sub < 2; ++sub)
; #pragma unroll
;         for (int s2 = 0; s2 < 2; ++s2) {
;             const bf16x8 pfa = pack8h(sub ? a1 : a0, s2), pfb = pack8h(sub ? b1 : b0, s2);
;             const LAS unsigned char* qa = va + voff + (32 * sub + 16 * s2) * 128; const LAS unsigned char* qb = vbb + voff + (32 * sub + 16 * s2) * 128;
;             { const s16x4 lo = vtr(qa + vx), hi = vtr(qa + 1024 + vx); const bf16x8 vf = {lo[0], lo[1], lo[2], lo[3], hi[0], hi[1], hi[2], hi[3]}; sa.o0 = MFMA32(vf, pfa, sa.o0); }
;             { const s16x4 lo = vtr(qb + vx), hi = vtr(qb + 1024 + vx); const bf16x8 vf = {lo[0], lo[1], lo[2], lo[3], hi[0], hi[1], hi[2], hi[3]}; sb.o0 = MFMA32(vf, pfb, sb.o0); }
;             { const s16x4 lo = vtr(qa + (64 - vx)), hi = vtr(qa + 1024 + (64 - vx)); const bf16x8 vf = {lo[0], lo[1], lo[2], lo[3], hi[0], hi[1], hi[2], hi[3]}; sa.o1 = MFMA32(vf, pfa, sa.o1); }
;             { const s16x4 lo = vtr(qb + (64 - vx)), hi = vtr(qb + 1024 + (64 - vx)); const bf16x8 vf = {lo[0], lo[1], lo[2], lo[3], hi[0], hi[1], hi[2], hi[3]}; sb.o1 = MFMA32(vf, pfb, sb.o1); }
	v_mfma_f32_32x32x16_bf16 v[4:19], v[222:225], v[122:125], v[4:19]
	v_exp_f32_e32 v100, v70
	v_exp_f32_e32 v131, v68
	ds_read_b64_tr_b16 v[122:123], v72 offset:26688
	ds_read_b64_tr_b16 v[124:125], v72 offset:27712
	v_cvt_pk_bf16_f32 v126, v74, v76
	v_cvt_pk_bf16_f32 v127, v92, v78
	v_cvt_pk_bf16_f32 v128, v112, v248
	v_cvt_pk_bf16_f32 v129, v84, v100
	s_waitcnt lgkmcnt(4)
	v_mfma_f32_32x32x16_bf16 v[20:35], v[230:233], v[226:229], v[20:35]
	v_cvt_pk_bf16_f32 v222, v105, v107
	v_cvt_pk_bf16_f32 v223, v109, v111
	v_cvt_pk_bf16_f32 v224, v247, v251
	v_cvt_pk_bf16_f32 v225, v189, v131
	v_fma_f32 v68, s4, v94, v187
	v_exp_f32_e32 v93, v68
	v_fmamk_f32 v68, v79, 0x3e38aa3b, v221
	v_mfma_f32_32x32x16_bf16 v[52:67], v[234:237], v[126:129], v[52:67]
	v_exp_f32_e32 v110, v68
	v_fma_f32 v68, s4, v95, v187
	v_exp_f32_e32 v79, v68
	v_fmamk_f32 v68, v80, 0x3e38aa3b, v221
	v_exp_f32_e32 v246, v68
	v_fma_f32 v68, s4, v96, v187
	v_exp_f32_e32 v113, v68
	v_mfma_f32_32x32x16_bf16 v[36:51], v[238:241], v[222:225], v[36:51]
	v_fmamk_f32 v68, v81, 0x3e38aa3b, v221
	v_cvt_pk_bf16_f32 v95, v116, v118
	v_exp_f32_e32 v250, v68
	v_fma_f32 v68, s4, v97, v187
	v_exp_f32_e32 v249, v68
	v_cvt_pk_bf16_f32 v94, v184, v188
	v_cvt_pk_bf16_f32 v96, v190, v192
	s_waitcnt lgkmcnt(2)
	v_mfma_f32_32x32x16_bf16 v[4:19], v[242:245], v[126:129], v[4:19]
	v_cvt_pk_bf16_f32 v97, v196, v102
	v_cvt_pk_bf16_f32 v68, v183, v101
	v_cvt_pk_bf16_f32 v69, v69, v71
	v_cvt_pk_bf16_f32 v70, v85, v73
	v_cvt_pk_bf16_f32 v71, v121, v91
	v_add_f32_e32 v86, v88, v86
	v_add_f32_e32 v87, v89, v87
	v_add_f32_e32 v88, v120, v196
	v_add_f32_e32 v89, v121, v197
	s_waitcnt lgkmcnt(0)
	v_mfma_f32_32x32x16_bf16 v[20:35], v[122:125], v[222:225], v[20:35]
	ds_read_b64_tr_b16 v[122:123], v182 offset:12288
	ds_read_b64_tr_b16 v[124:125], v182 offset:13312
	ds_read_b64_tr_b16 v[114:115], v182 offset:28672
	ds_read_b64_tr_b16 v[116:117], v182 offset:29696
	ds_read_b64_tr_b16 v[126:127], v182 offset:14336
	ds_read_b64_tr_b16 v[128:129], v182 offset:15360
	v_fmamk_f32 v73, v82, 0x3e38aa3b, v221
	v_exp_f32_e32 v75, v75
	v_exp_f32_e32 v188, v73
	v_fma_f32 v73, s4, v98, v187
	v_fmac_f32_e32 v221, 0x3e38aa3b, v83
	s_waitcnt lgkmcnt(4)
	v_mfma_f32_32x32x16_bf16 v[52:67], v[122:125], v[94:97], v[52:67]
	ds_read_b64_tr_b16 v[118:119], v72 offset:12352
	ds_read_b64_tr_b16 v[120:121], v72 offset:13376
	ds_read_b64_tr_b16 v[122:123], v182 offset:30720
	ds_read_b64_tr_b16 v[124:125], v182 offset:31744
	v_fmac_f32_e32 v187, s4, v99
	v_exp_f32_e32 v77, v77
	v_exp_f32_e32 v85, v73
	v_exp_f32_e32 v130, v221
	v_exp_f32_e32 v101, v187
	s_add_u32 s52, s52, 16
	s_waitcnt lgkmcnt(6)
	v_mfma_f32_32x32x16_bf16 v[36:51], v[114:117], v[68:71], v[36:51]
	ds_read_b64_tr_b16 v[114:115], v72 offset:28736
	ds_read_b64_tr_b16 v[116:117], v72 offset:29760
	ds_read_b64_tr_b16 v[182:183], v72 offset:14400
	ds_read_b64_tr_b16 v[184:185], v72 offset:15424
	ds_read_b64_tr_b16 v[80:81], v72 offset:30784
	ds_read_b64_tr_b16 v[82:83], v72 offset:31808
	s_addc_u32 s53, s53, 0
	v_lshl_add_u64 v[174:175], v[174:175], 0, s[48:49]
	s_cmp_lg_u32 s72, s50
	v_lshl_add_u64 v[176:177], v[176:177], 0, s[48:49]
	s_waitcnt lgkmcnt(8)
	v_mfma_f32_32x32x16_bf16 v[4:19], v[118:121], v[94:97], v[4:19]
	s_waitcnt lgkmcnt(4)
	v_mfma_f32_32x32x16_bf16 v[20:35], v[114:117], v[68:71], v[20:35]
	v_add_f32_e64 v68, v88, v86
	v_add_f32_e64 v69, v89, v87
	v_add_f32_e64 v70, v90, v102
	v_add_f32_e64 v71, v91, v103
	v_add_f32_e64 v86, v74, v104
	v_add_f32_e64 v87, v75, v105
	v_add_f32_e32 v72, v70, v68
	v_add_f32_e32 v73, v71, v69
	v_cvt_pk_bf16_f32 v68, v104, v106
	v_cvt_pk_bf16_f32 v69, v108, v110
	v_cvt_pk_bf16_f32 v70, v246, v250
	v_cvt_pk_bf16_f32 v71, v188, v130
	v_add_f32_e32 v86, v86, v72
	v_add_f32_e32 v87, v87, v73
	v_add_f32_e32 v88, v76, v106
	v_add_f32_e32 v89, v77, v107
	v_cvt_pk_bf16_f32 v72, v75, v77
	v_cvt_pk_bf16_f32 v73, v93, v79
	v_cvt_pk_bf16_f32 v74, v113, v249
	v_cvt_pk_bf16_f32 v75, v85, v101
	v_mfma_f32_32x32x16_bf16 v[52:67], v[126:129], v[68:71], v[52:67]
	v_add_f32_e64 v76, v88, v86
	v_add_f32_e64 v77, v89, v87
	v_add_f32_e64 v86, v92, v108
	v_add_f32_e64 v87, v93, v109
	v_add_f32_e64 v78, v78, v110
	v_add_f32_e64 v79, v79, v111
	v_add_f32_e32 v76, v86, v76
	v_add_f32_e32 v77, v87, v77
	s_nop 0
	v_add_f32_e32 v76, v78, v76
	v_add_f32_e32 v77, v79, v77
	v_add_f32_e32 v78, v112, v246
	v_add_f32_e32 v79, v113, v247
	v_mfma_f32_32x32x16_bf16 v[36:51], v[122:125], v[72:75], v[36:51]
	v_add_f32_e64 v76, v78, v76
	v_add_f32_e64 v77, v79, v77
	s_waitcnt lgkmcnt(2)
	v_mfma_f32_32x32x16_bf16 v[4:19], v[182:185], v[68:71], v[4:19]
	v_add_f32_e64 v68, v248, v250
	v_add_f32_e64 v69, v249, v251
	v_add_f32_e64 v70, v84, v188
	v_add_f32_e64 v71, v85, v189
	v_add_f32_e64 v68, v68, v76
	v_add_f32_e64 v69, v69, v77
	v_add_f32_e32 v68, v70, v68
	v_add_f32_e32 v69, v71, v69
	v_add_f32_e32 v70, v100, v130
	v_add_f32_e32 v71, v101, v131
	s_waitcnt lgkmcnt(0)
	v_mfma_f32_32x32x16_bf16 v[20:35], v[80:83], v[72:75], v[20:35]
	v_add_f32_e64 v68, v70, v68
	v_add_f32_e64 v69, v71, v69
	v_add_f32_e64 v172, v172, v68
	v_add_f32_e64 v173, v173, v69
	s_cbranch_scc0 .LBB0_735
	s_branch .LBB0_718

; #define LAS __attribute__((address_space(3)))
; #define MFMA32(a, b, c) __builtin_amdgcn_mfma_f32_32x32x16_bf16((a), (b), (c), 0, 0, 0)
; DI float fexp2(float x) { return __builtin_amdgcn_exp2f(x); }
; DI s16x4 vtr(const LAS unsigned char* p) { return __builtin_bit_cast(s16x4, __builtin_amdgcn_ds_read_tr16_b64_v4i16((LAS v4i16_t*)p)); }
; DI void flash_pv(FState& st, f32x16& p0, f32x16& p1, bool rowon, const LAS unsigned char* vb, int lane) {
;     ...
;     const float cl = rowon ? SM_C : 0.0f;
;     const float bl = rowon ? ((st.m == NINF) ? 0.0f : -st.m * SM_C) : NINF;
;     float sum = 0.f;
; #pragma unroll
;     for (int r = 0; r < 16; ++r) { p0[r] = fexp2(__builtin_fmaf(p0[r], cl, bl)); p1[r] = fexp2(__builtin_fmaf(p1[r], cl, bl)); sum += p0[r] + p1[r]; }
;     st.l += sum;
;     const int h = lane >> 5;
;     const int vx = (((lane & 15) >> 3) & 1) * 64;
;     const LAS unsigned char* vp = vb + (4 * h + ((lane & 15) >> 2)) * 128 + ((lane >> 4) & 1) * 32 + (lane & 3) * 8;
; #pragma unroll
;     for (int sub = 0; sub < 2; ++sub)
; #pragma unroll
;         for (int s2 = 0; s2 < 2; ++s2) {
;             const bf16x8 pf = pack8h(sub ? p1 : p0, s2);
;             const LAS unsigned char* vq = vp + (32 * sub + 16 * s2) * 128;
;             { const s16x4 lo = vtr(vq + vx), hi = vtr(vq + 1024 + vx); const bf16x8 vf = {lo[0], lo[1], lo[2], lo[3], hi[0], hi[1], hi[2], hi[3]}; st.o0 = MFMA32(vf, pf, st.o0); }
;             { const s16x4 lo = vtr(vq + (64 - vx)), hi = vtr(vq + 1024 + (64 - vx)); const bf16x8 vf = {lo[0], lo[1], lo[2], lo[3], hi[0], hi[1], hi[2], hi[3]}; st.o1 = MFMA32(vf, pf, st.o1); }
.LBB0_759:
	s_or_b64 exec, exec, s[4:5]
	v_fma_f32 v2, v98, v5, v4
	v_exp_f32_e32 v12, v2
	v_fma_f32 v2, v82, v5, v4
	v_exp_f32_e32 v246, v2
	s_waitcnt lgkmcnt(3)
	v_mfma_f32_32x32x16_bf16 v[130:145], v[226:229], v[154:157], v[130:145]
	v_fma_f32 v2, v99, v5, v4
	v_exp_f32_e32 v6, v2
	v_fma_f32 v2, v83, v5, v4
	v_exp_f32_e32 v2, v2
	v_add_f32_e32 v7, v12, v246
	s_add_i32 s77, s74, 1
	s_cmp_ge_u32 s77, s51
	v_add_f32_e32 v8, v6, v2
	v_add_f32_e32 v9, v7, v3
	v_fma_f32 v7, v100, v5, v4
	v_add_f32_e32 v99, v8, v9
	s_waitcnt lgkmcnt(2)
	v_mfma_f32_32x32x16_bf16 v[114:129], v[230:233], v[154:157], v[114:129]
	v_fma_f32 v8, v84, v5, v4
	v_exp_f32_e32 v7, v7
	v_exp_f32_e32 v247, v8
	v_fma_f32 v8, v101, v5, v4
	v_fma_f32 v9, v85, v5, v4
	v_exp_f32_e32 v8, v8
	v_exp_f32_e32 v98, v9
	v_add_f32_e32 v9, v7, v247
	v_cvt_pk_bf16_f32 v6, v12, v6
	v_cvt_pk_bf16_f32 v7, v7, v8
	s_waitcnt lgkmcnt(1)
	v_mfma_f32_32x32x16_bf16 v[130:145], v[234:237], v[158:161], v[130:145]
	v_add_f32_e32 v10, v8, v98
	v_add_f32_e32 v11, v9, v99
	v_fma_f32 v9, v102, v5, v4
	v_add_f32_e32 v101, v10, v11
	v_fma_f32 v10, v86, v5, v4
	v_exp_f32_e32 v99, v10
	v_fma_f32 v10, v103, v5, v4
	v_exp_f32_e32 v9, v9
	v_exp_f32_e32 v14, v10
	v_fma_f32 v10, v87, v5, v4
	v_exp_f32_e32 v100, v10
	s_waitcnt lgkmcnt(0)
	v_mfma_f32_32x32x16_bf16 v[114:129], v[238:241], v[158:161], v[114:129]
	v_add_f32_e32 v15, v9, v99
	v_cvt_pk_bf16_f32 v8, v9, v14
	v_add_f32_e32 v10, v14, v100
	v_add_f32_e32 v11, v15, v101
	s_nop 0
	v_add_f32_e32 v87, v10, v11
	v_fma_f32 v10, v104, v5, v4
	v_exp_f32_e32 v15, v10
	v_fma_f32 v10, v88, v5, v4
	v_exp_f32_e32 v101, v10
	v_fma_f32 v10, v105, v5, v4
	v_exp_f32_e32 v16, v10
	v_fma_f32 v10, v89, v5, v4
	v_exp_f32_e32 v86, v10
	v_add_f32_e32 v17, v15, v101
	v_cvt_pk_bf16_f32 v9, v15, v16
	v_add_f32_e32 v10, v16, v86
	v_add_f32_e32 v11, v17, v87
	s_nop 0
	v_add_f32_e32 v89, v10, v11
	v_fma_f32 v10, v106, v5, v4
	v_exp_f32_e32 v87, v10
	v_fma_f32 v10, v90, v5, v4
	v_exp_f32_e32 v248, v10
	v_fma_f32 v10, v107, v5, v4
	v_exp_f32_e32 v90, v10
	v_fma_f32 v10, v91, v5, v4
	v_exp_f32_e32 v88, v10
	v_fma_f32 v10, v108, v5, v4
	v_exp_f32_e32 v107, v10
	v_fma_f32 v10, v92, v5, v4
	v_add_f32_e32 v91, v87, v248
	v_exp_f32_e32 v108, v10
	v_add_f32_e32 v10, v90, v88
	v_add_f32_e32 v11, v91, v89
	v_fma_f32 v91, v112, v5, v4
	v_add_f32_e32 v103, v10, v11
	v_fma_f32 v10, v109, v5, v4
	v_exp_f32_e32 v104, v10
	v_fma_f32 v10, v93, v5, v4
	v_exp_f32_e32 v102, v10
	ds_read_b64_tr_b16 v[10:11], v218 offset:8192
	ds_read_b64_tr_b16 v[12:13], v218 offset:9216
	ds_read_b64_tr_b16 v[14:15], v217 offset:8256
	ds_read_b64_tr_b16 v[16:17], v217 offset:9280
	ds_read_b64_tr_b16 v[82:83], v218 offset:10240
	ds_read_b64_tr_b16 v[84:85], v218 offset:11264
	s_waitcnt lgkmcnt(4)
	v_mfma_f32_32x32x16_bf16 v[66:81], v[10:13], v[6:9], v[66:81]
	v_fma_f32 v10, v110, v5, v4
	v_exp_f32_e32 v89, v10
	v_fma_f32 v10, v111, v5, v4
	v_exp_f32_e32 v92, v10
	v_exp_f32_e32 v109, v91
	v_add_f32_e32 v105, v107, v108
	ds_read_b64_tr_b16 v[10:11], v217 offset:10304
	ds_read_b64_tr_b16 v[12:13], v217 offset:11328
	s_waitcnt lgkmcnt(4)
	v_mfma_f32_32x32x16_bf16 v[50:65], v[14:17], v[6:9], v[50:65]
	v_fma_f32 v6, v113, v5, v4
	v_exp_f32_e32 v106, v6
	v_cvt_pk_bf16_f32 v6, v87, v90
	v_cvt_pk_bf16_f32 v7, v107, v104
	v_cvt_pk_bf16_f32 v8, v89, v92
	v_cvt_pk_bf16_f32 v9, v109, v106
	v_add_f32_e32 v14, v104, v102
	v_add_f32_e32 v15, v105, v103
	s_waitcnt lgkmcnt(2)
	v_mfma_f32_32x32x16_bf16 v[66:81], v[82:85], v[6:9], v[66:81]
	v_add_f32_e64 v91, v14, v15
	v_fma_f32 v14, v94, v5, v4
	v_exp_f32_e32 v94, v14
	ds_read_b64_tr_b16 v[14:15], v218 offset:12288
	ds_read_b64_tr_b16 v[16:17], v218 offset:13312
	v_fma_f32 v82, v95, v5, v4
	v_exp_f32_e32 v90, v82
	v_add_f32_e32 v93, v89, v94
	s_waitcnt lgkmcnt(2)
	v_mfma_f32_32x32x16_bf16 v[50:65], v[10:13], v[6:9], v[50:65]
	v_cvt_pk_bf16_f32 v6, v246, v2
	v_cvt_pk_bf16_f32 v7, v247, v98
	v_cvt_pk_bf16_f32 v8, v99, v100
	v_cvt_pk_bf16_f32 v9, v101, v86
	ds_read_b64_tr_b16 v[10:11], v218 offset:14336
	ds_read_b64_tr_b16 v[12:13], v218 offset:15360
	v_add_f32_e32 v82, v92, v90
	v_add_f32_e32 v83, v93, v91
	v_fma_f32 v2, v96, v5, v4
	s_waitcnt lgkmcnt(2)
	v_mfma_f32_32x32x16_bf16 v[66:81], v[14:17], v[6:9], v[66:81]
	ds_read_b64_tr_b16 v[14:15], v217 offset:12352
	ds_read_b64_tr_b16 v[16:17], v217 offset:13376
	v_add_f32_e64 v87, v82, v83
	v_fmac_f32_e32 v4, v97, v5
	ds_read_b64_tr_b16 v[82:83], v217 offset:14400
	ds_read_b64_tr_b16 v[84:85], v217 offset:15424
	v_exp_f32_e32 v2, v2
	v_exp_f32_e32 v86, v4
	v_cvt_pk_bf16_f32 v4, v248, v88
	s_waitcnt lgkmcnt(2)
	v_mfma_f32_32x32x16_bf16 v[50:65], v[14:17], v[6:9], v[50:65]
	v_cvt_pk_bf16_f32 v5, v108, v102
	v_cvt_pk_bf16_f32 v6, v94, v90
	v_cvt_pk_bf16_f32 v7, v2, v86
	v_add_f32_e32 v107, v109, v2
	v_add_f32_e64 v8, v106, v86
	v_add_f32_e64 v9, v107, v87
	v_add_f32_e32 v2, v8, v9
	v_mfma_f32_32x32x16_bf16 v[66:81], v[10:13], v[4:7], v[66:81]
	v_add_f32_e32 v214, v214, v2
	s_waitcnt lgkmcnt(0)
	v_mfma_f32_32x32x16_bf16 v[50:65], v[82:85], v[4:7], v[50:65]
	s_cbranch_scc1 .LBB0_780
	s_movk_i32 s76, 0x4000
	s_add_i32 s4, s74, 5
	s_cmp_ge_u32 s4, s51
	s_waitcnt vmcnt(1)
	ds_write_b128 v205, v[182:185] offset:32768
	s_waitcnt vmcnt(0)
	ds_write_b128 v212, v[178:181] offset:40960
	s_waitcnt lgkmcnt(0)
	s_barrier
	s_cbranch_scc1 .LBB0_762
	s_cmp_gt_u32 s4, s69
	s_cselect_b64 s[8:9], -1, 0
	s_mov_b32 s5, s52
	s_and_b64 s[8:9], s[8:9], exec
	s_cselect_b32 s4, s5, s4
	s_cselect_b32 s16, 0x1000, s65
	s_cselect_b32 s8, s64, 0x500
	s_lshl_b32 s4, s4, 6
	s_mov_b32 s9, s17
	v_mad_i64_i32 v[4:5], s[4:5], s4, v199, v[192:193]
	v_lshl_add_u64 v[6:7], v[4:5], 0, s[8:9]
	v_lshl_add_u64 v[4:5], v[4:5], 0, s[16:17]
	global_load_dwordx4 v[182:185], v[6:7], off
	global_load_dwordx4 v[178:181], v[4:5], off

; #define LAS __attribute__((address_space(3)))
; #define MFMA32(a, b, c) __builtin_amdgcn_mfma_f32_32x32x16_bf16((a), (b), (c), 0, 0, 0)
; DI float fexp2(float x) { return __builtin_amdgcn_exp2f(x); }
; DI s16x4 vtr(const LAS unsigned char* p) { return __builtin_bit_cast(s16x4, __builtin_amdgcn_ds_read_tr16_b64_v4i16((LAS v4i16_t*)p)); }
; DI void flash_pv(FState& st, f32x16& p0, f32x16& p1, bool rowon, const LAS unsigned char* vb, int lane) {
;     ...
;     const float cl = rowon ? SM_C : 0.0f;
;     const float bl = rowon ? ((st.m == NINF) ? 0.0f : -st.m * SM_C) : NINF;
;     float sum = 0.f;
; #pragma unroll
;     for (int r = 0; r < 16; ++r) { p0[r] = fexp2(__builtin_fmaf(p0[r], cl, bl)); p1[r] = fexp2(__builtin_fmaf(p1[r], cl, bl)); sum += p0[r] + p1[r]; }
;     st.l += sum;
;     const int h = lane >> 5;
;     const int vx = (((lane & 15) >> 3) & 1) * 64;
;     const LAS unsigned char* vp = vb + (4 * h + ((lane & 15) >> 2)) * 128 + ((lane >> 4) & 1) * 32 + (lane & 3) * 8;
; #pragma unroll
;     for (int sub = 0; sub < 2; ++sub)
; #pragma unroll
;         for (int s2 = 0; s2 < 2; ++s2) {
;             const bf16x8 pf = pack8h(sub ? p1 : p0, s2);
;             const LAS unsigned char* vq = vp + (32 * sub + 16 * s2) * 128;
;             { const s16x4 lo = vtr(vq + vx), hi = vtr(vq + 1024 + vx); const bf16x8 vf = {lo[0], lo[1], lo[2], lo[3], hi[0], hi[1], hi[2], hi[3]}; st.o0 = MFMA32(vf, pf, st.o0); }
;             { const s16x4 lo = vtr(vq + (64 - vx)), hi = vtr(vq + 1024 + (64 - vx)); const bf16x8 vf = {lo[0], lo[1], lo[2], lo[3], hi[0], hi[1], hi[2], hi[3]}; st.o1 = MFMA32(vf, pf, st.o1); }
.LBB0_778:
	s_or_b64 exec, exec, s[4:5]
	v_fma_f32 v2, v130, v5, v4
	v_exp_f32_e32 v12, v2
	v_fma_f32 v2, v114, v5, v4
	v_exp_f32_e32 v246, v2
	s_waitcnt lgkmcnt(3)
	v_mfma_f32_32x32x16_bf16 v[98:113], v[226:229], v[154:157], v[98:113]
	v_fma_f32 v2, v131, v5, v4
	v_exp_f32_e32 v6, v2
	v_fma_f32 v2, v115, v5, v4
	v_exp_f32_e32 v2, v2
	v_add_f32_e32 v7, v12, v246
	v_add_f32_e32 v8, v6, v2
	v_add_f32_e32 v9, v7, v3
	s_nop 0
	v_add_f32_e32 v131, v8, v9
	v_fma_f32 v7, v132, v5, v4
	v_fma_f32 v8, v116, v5, v4
	s_waitcnt lgkmcnt(2)
	v_mfma_f32_32x32x16_bf16 v[82:97], v[230:233], v[154:157], v[82:97]
	v_exp_f32_e32 v7, v7
	v_exp_f32_e32 v247, v8
	v_fma_f32 v8, v133, v5, v4
	v_fma_f32 v9, v117, v5, v4
	v_exp_f32_e32 v8, v8
	v_exp_f32_e32 v130, v9
	v_add_f32_e32 v9, v7, v247
	v_cvt_pk_bf16_f32 v6, v12, v6
	v_cvt_pk_bf16_f32 v7, v7, v8
	v_add_f32_e32 v10, v8, v130
	v_add_f32_e32 v11, v9, v131
	s_waitcnt lgkmcnt(1)
	v_mfma_f32_32x32x16_bf16 v[98:113], v[234:237], v[158:161], v[98:113]
	v_fma_f32 v9, v134, v5, v4
	v_add_f32_e32 v133, v10, v11
	v_fma_f32 v10, v118, v5, v4
	v_exp_f32_e32 v131, v10
	v_fma_f32 v10, v135, v5, v4
	v_exp_f32_e32 v9, v9
	v_exp_f32_e32 v14, v10
	v_fma_f32 v10, v119, v5, v4
	v_exp_f32_e32 v132, v10
	v_add_f32_e32 v15, v9, v131
	s_waitcnt lgkmcnt(0)
	v_mfma_f32_32x32x16_bf16 v[82:97], v[238:241], v[158:161], v[82:97]
	v_cvt_pk_bf16_f32 v8, v9, v14
	v_add_f32_e32 v10, v14, v132
	v_add_f32_e32 v11, v15, v133
	s_nop 0
	v_add_f32_e32 v119, v10, v11
	v_fma_f32 v10, v136, v5, v4
	v_exp_f32_e32 v15, v10
	v_fma_f32 v10, v120, v5, v4
	v_exp_f32_e32 v133, v10
	v_fma_f32 v10, v137, v5, v4
	v_exp_f32_e32 v16, v10
	v_fma_f32 v10, v121, v5, v4
	v_exp_f32_e32 v118, v10
	v_add_f32_e32 v17, v15, v133
	v_cvt_pk_bf16_f32 v9, v15, v16
	v_add_f32_e32 v10, v16, v118
	v_add_f32_e32 v11, v17, v119
	s_nop 0
	v_add_f32_e32 v121, v10, v11
	v_fma_f32 v10, v138, v5, v4
	v_exp_f32_e32 v119, v10
	v_fma_f32 v10, v122, v5, v4
	v_exp_f32_e32 v248, v10
	v_fma_f32 v10, v139, v5, v4
	v_exp_f32_e32 v122, v10
	v_fma_f32 v10, v123, v5, v4
	v_exp_f32_e32 v120, v10
	v_fma_f32 v10, v140, v5, v4
	v_exp_f32_e32 v139, v10
	v_fma_f32 v10, v124, v5, v4
	v_add_f32_e32 v123, v119, v248
	v_exp_f32_e32 v140, v10
	v_add_f32_e32 v10, v122, v120
	v_add_f32_e32 v11, v123, v121
	v_fma_f32 v123, v144, v5, v4
	v_add_f32_e32 v135, v10, v11
	v_fma_f32 v10, v141, v5, v4
	v_exp_f32_e32 v136, v10
	v_fma_f32 v10, v125, v5, v4
	v_exp_f32_e32 v134, v10
	ds_read_b64_tr_b16 v[10:11], v218 offset:24576
	ds_read_b64_tr_b16 v[12:13], v218 offset:25600
	ds_read_b64_tr_b16 v[14:15], v217 offset:24640
	ds_read_b64_tr_b16 v[16:17], v217 offset:25664
	ds_read_b64_tr_b16 v[114:115], v218 offset:26624
	ds_read_b64_tr_b16 v[116:117], v218 offset:27648
	s_waitcnt lgkmcnt(4)
	v_mfma_f32_32x32x16_bf16 v[66:81], v[10:13], v[6:9], v[66:81]
	v_fma_f32 v10, v142, v5, v4
	v_exp_f32_e32 v125, v10
	v_fma_f32 v10, v143, v5, v4
	v_exp_f32_e32 v124, v10
	v_exp_f32_e32 v142, v123
	v_add_f32_e32 v137, v139, v140
	ds_read_b64_tr_b16 v[10:11], v217 offset:26688
	ds_read_b64_tr_b16 v[12:13], v217 offset:27712
	s_waitcnt lgkmcnt(4)
	v_mfma_f32_32x32x16_bf16 v[50:65], v[14:17], v[6:9], v[50:65]
	v_fma_f32 v6, v145, v5, v4
	v_exp_f32_e32 v138, v6
	v_cvt_pk_bf16_f32 v6, v119, v122
	v_cvt_pk_bf16_f32 v7, v139, v136
	v_cvt_pk_bf16_f32 v8, v125, v124
	v_cvt_pk_bf16_f32 v9, v142, v138
	v_add_f32_e32 v14, v136, v134
	v_add_f32_e32 v15, v137, v135
	s_waitcnt lgkmcnt(2)
	v_mfma_f32_32x32x16_bf16 v[66:81], v[114:117], v[6:9], v[66:81]
	v_add_f32_e64 v123, v14, v15
	v_fma_f32 v14, v126, v5, v4
	v_exp_f32_e32 v126, v14
	ds_read_b64_tr_b16 v[14:15], v218 offset:28672
	ds_read_b64_tr_b16 v[16:17], v218 offset:29696
	v_fma_f32 v114, v127, v5, v4
	v_exp_f32_e32 v122, v114
	v_add_f32_e32 v125, v125, v126
	s_waitcnt lgkmcnt(2)
	v_mfma_f32_32x32x16_bf16 v[50:65], v[10:13], v[6:9], v[50:65]
	v_cvt_pk_bf16_f32 v6, v246, v2
	v_cvt_pk_bf16_f32 v7, v247, v130
	v_cvt_pk_bf16_f32 v8, v131, v132
	v_cvt_pk_bf16_f32 v9, v133, v118
	ds_read_b64_tr_b16 v[10:11], v218 offset:30720
	ds_read_b64_tr_b16 v[12:13], v218 offset:31744
	v_add_f32_e32 v114, v124, v122
	v_add_f32_e32 v115, v125, v123
	v_fma_f32 v2, v128, v5, v4
	s_waitcnt lgkmcnt(2)
	v_mfma_f32_32x32x16_bf16 v[66:81], v[14:17], v[6:9], v[66:81]
	ds_read_b64_tr_b16 v[14:15], v217 offset:28736
	ds_read_b64_tr_b16 v[16:17], v217 offset:29760
	v_add_f32_e64 v119, v114, v115
	v_fmac_f32_e32 v4, v129, v5
	ds_read_b64_tr_b16 v[114:115], v217 offset:30784
	ds_read_b64_tr_b16 v[116:117], v217 offset:31808
	v_exp_f32_e32 v2, v2
	v_exp_f32_e32 v118, v4
	v_cvt_pk_bf16_f32 v4, v248, v120
	s_waitcnt lgkmcnt(2)
	v_mfma_f32_32x32x16_bf16 v[50:65], v[14:17], v[6:9], v[50:65]
	v_cvt_pk_bf16_f32 v5, v140, v134
	v_cvt_pk_bf16_f32 v6, v126, v122
	v_cvt_pk_bf16_f32 v7, v2, v118
	v_add_f32_e32 v139, v142, v2
	v_add_f32_e64 v8, v138, v118
	v_add_f32_e64 v9, v139, v119
	v_add_f32_e32 v2, v8, v9
	v_mfma_f32_32x32x16_bf16 v[66:81], v[10:13], v[4:7], v[66:81]
	v_add_f32_e32 v214, v214, v2
	s_waitcnt lgkmcnt(0)
	v_mfma_f32_32x32x16_bf16 v[50:65], v[114:117], v[4:7], v[50:65]
	s_add_i32 s76, s74, 2
	s_cmp_ge_u32 s76, s51
	s_cbranch_scc0 .LBB0_781

; #define LAS __attribute__((address_space(3)))
; #define MFMA32(a, b, c) __builtin_amdgcn_mfma_f32_32x32x16_bf16((a), (b), (c), 0, 0, 0)
; DI float fexp2(float x) { return __builtin_amdgcn_exp2f(x); }
; DI s16x4 vtr(const LAS unsigned char* p) { return __builtin_bit_cast(s16x4, __builtin_amdgcn_ds_read_tr16_b64_v4i16((LAS v4i16_t*)p)); }
; DI void flash_pv(FState& st, f32x16& p0, f32x16& p1, bool rowon, const LAS unsigned char* vb, int lane) {
;     ...
;     const float cl = rowon ? SM_C : 0.0f;
;     const float bl = rowon ? ((st.m == NINF) ? 0.0f : -st.m * SM_C) : NINF;
;     float sum = 0.f;
; #pragma unroll
;     for (int r = 0; r < 16; ++r) { p0[r] = fexp2(__builtin_fmaf(p0[r], cl, bl)); p1[r] = fexp2(__builtin_fmaf(p1[r], cl, bl)); sum += p0[r] + p1[r]; }
;     st.l += sum;
;     const int h = lane >> 5;
;     const int vx = (((lane & 15) >> 3) & 1) * 64;
;     const LAS unsigned char* vp = vb + (4 * h + ((lane & 15) >> 2)) * 128 + ((lane >> 4) & 1) * 32 + (lane & 3) * 8;
; #pragma unroll
;     for (int sub = 0; sub < 2; ++sub)
; #pragma unroll
;         for (int s2 = 0; s2 < 2; ++s2) {
;             const bf16x8 pf = pack8h(sub ? p1 : p0, s2);
;             const LAS unsigned char* vq = vp + (32 * sub + 16 * s2) * 128;
;             { const s16x4 lo = vtr(vq + vx), hi = vtr(vq + 1024 + vx); const bf16x8 vf = {lo[0], lo[1], lo[2], lo[3], hi[0], hi[1], hi[2], hi[3]}; st.o0 = MFMA32(vf, pf, st.o0); }
;             { const s16x4 lo = vtr(vq + (64 - vx)), hi = vtr(vq + 1024 + (64 - vx)); const bf16x8 vf = {lo[0], lo[1], lo[2], lo[3], hi[0], hi[1], hi[2], hi[3]}; st.o1 = MFMA32(vf, pf, st.o1); }
.LBB0_799:
	s_or_b64 exec, exec, s[4:5]
	v_fma_f32 v2, v98, v5, v4
	v_exp_f32_e32 v246, v2
	v_fma_f32 v2, v82, v5, v4
	v_exp_f32_e32 v247, v2
	s_waitcnt lgkmcnt(3)
	v_mfma_f32_32x32x16_bf16 v[130:145], v[226:229], v[154:157], v[130:145]
	v_fma_f32 v2, v99, v5, v4
	v_exp_f32_e32 v10, v2
	v_fma_f32 v2, v83, v5, v4
	v_exp_f32_e32 v2, v2
	v_add_f32_e32 v11, v246, v247
	v_add_f32_e32 v6, v10, v2
	v_add_f32_e32 v7, v11, v3
	s_nop 0
	v_add_f32_e32 v99, v6, v7
	v_fma_f32 v6, v100, v5, v4
	v_exp_f32_e32 v11, v6
	s_waitcnt lgkmcnt(2)
	v_mfma_f32_32x32x16_bf16 v[114:129], v[230:233], v[154:157], v[114:129]
	v_fma_f32 v6, v84, v5, v4
	v_exp_f32_e32 v248, v6
	v_fma_f32 v6, v101, v5, v4
	v_exp_f32_e32 v12, v6
	v_fma_f32 v6, v85, v5, v4
	v_exp_f32_e32 v98, v6
	v_add_f32_e32 v13, v11, v248
	v_cvt_pk_bf16_f32 v10, v246, v10
	v_cvt_pk_bf16_f32 v11, v11, v12
	v_add_f32_e32 v6, v12, v98
	v_add_f32_e32 v7, v13, v99
	s_waitcnt lgkmcnt(1)
	v_mfma_f32_32x32x16_bf16 v[130:145], v[234:237], v[158:161], v[130:145]
	s_nop 0
	v_add_f32_e32 v101, v6, v7
	v_fma_f32 v6, v102, v5, v4
	v_exp_f32_e32 v13, v6
	v_fma_f32 v6, v86, v5, v4
	v_exp_f32_e32 v99, v6
	v_fma_f32 v6, v103, v5, v4
	v_exp_f32_e32 v14, v6
	v_fma_f32 v6, v87, v5, v4
	v_exp_f32_e32 v100, v6
	s_waitcnt lgkmcnt(0)
	v_mfma_f32_32x32x16_bf16 v[114:129], v[238:241], v[158:161], v[114:129]
	v_add_f32_e32 v15, v13, v99
	v_cvt_pk_bf16_f32 v12, v13, v14
	v_add_f32_e32 v6, v14, v100
	v_add_f32_e32 v7, v15, v101
	s_nop 0
	v_add_f32_e32 v87, v6, v7
	v_fma_f32 v6, v104, v5, v4
	v_exp_f32_e32 v15, v6
	v_fma_f32 v6, v88, v5, v4
	v_exp_f32_e32 v101, v6
	v_fma_f32 v6, v105, v5, v4
	v_exp_f32_e32 v16, v6
	v_fma_f32 v6, v89, v5, v4
	v_exp_f32_e32 v86, v6
	v_add_f32_e32 v17, v15, v101
	v_cvt_pk_bf16_f32 v13, v15, v16
	v_add_f32_e32 v6, v16, v86
	v_add_f32_e32 v7, v17, v87
	s_nop 0
	v_add_f32_e32 v89, v6, v7
	v_fma_f32 v6, v106, v5, v4
	v_exp_f32_e32 v87, v6
	v_fma_f32 v6, v90, v5, v4
	v_exp_f32_e32 v249, v6
	v_fma_f32 v6, v107, v5, v4
	v_exp_f32_e32 v90, v6
	v_fma_f32 v6, v91, v5, v4
	v_exp_f32_e32 v88, v6
	v_fma_f32 v6, v108, v5, v4
	v_exp_f32_e32 v107, v6
	v_fma_f32 v6, v92, v5, v4
	v_add_f32_e32 v91, v87, v249
	v_exp_f32_e32 v108, v6
	v_add_f32_e32 v6, v90, v88
	v_add_f32_e32 v7, v91, v89
	v_fma_f32 v91, v112, v5, v4
	v_add_f32_e32 v103, v6, v7
	v_fma_f32 v6, v109, v5, v4
	v_exp_f32_e32 v104, v6
	v_fma_f32 v6, v93, v5, v4
	v_exp_f32_e32 v102, v6
	ds_read_b64_tr_b16 v[6:7], v218 offset:40960
	ds_read_b64_tr_b16 v[8:9], v218 offset:41984
	ds_read_b64_tr_b16 v[14:15], v217 offset:41024
	ds_read_b64_tr_b16 v[16:17], v217 offset:42048
	ds_read_b64_tr_b16 v[82:83], v218 offset:43008
	ds_read_b64_tr_b16 v[84:85], v218 offset:44032
	s_waitcnt lgkmcnt(4)
	v_mfma_f32_32x32x16_bf16 v[66:81], v[6:9], v[10:13], v[66:81]
	v_fma_f32 v6, v110, v5, v4
	v_exp_f32_e32 v89, v6
	v_fma_f32 v6, v111, v5, v4
	v_exp_f32_e32 v92, v6
	v_exp_f32_e32 v109, v91
	v_add_f32_e32 v105, v107, v108
	ds_read_b64_tr_b16 v[6:7], v217 offset:43072
	ds_read_b64_tr_b16 v[8:9], v217 offset:44096
	s_waitcnt lgkmcnt(4)
	v_mfma_f32_32x32x16_bf16 v[50:65], v[14:17], v[10:13], v[50:65]
	v_fma_f32 v10, v113, v5, v4
	v_exp_f32_e32 v106, v10
	v_cvt_pk_bf16_f32 v10, v87, v90
	v_cvt_pk_bf16_f32 v11, v107, v104
	v_cvt_pk_bf16_f32 v12, v89, v92
	v_cvt_pk_bf16_f32 v13, v109, v106
	v_add_f32_e32 v14, v104, v102
	v_add_f32_e32 v15, v105, v103
	s_waitcnt lgkmcnt(2)
	v_mfma_f32_32x32x16_bf16 v[66:81], v[82:85], v[10:13], v[66:81]
	v_add_f32_e64 v91, v14, v15
	v_fma_f32 v14, v94, v5, v4
	v_exp_f32_e32 v94, v14
	ds_read_b64_tr_b16 v[14:15], v218 offset:45056
	ds_read_b64_tr_b16 v[16:17], v218 offset:46080
	v_fma_f32 v82, v95, v5, v4
	v_exp_f32_e32 v90, v82
	v_add_f32_e32 v93, v89, v94
	s_waitcnt lgkmcnt(2)
	v_mfma_f32_32x32x16_bf16 v[50:65], v[6:9], v[10:13], v[50:65]
	v_cvt_pk_bf16_f32 v6, v247, v2
	v_cvt_pk_bf16_f32 v7, v248, v98
	v_cvt_pk_bf16_f32 v8, v99, v100
	v_cvt_pk_bf16_f32 v9, v101, v86
	ds_read_b64_tr_b16 v[10:11], v218 offset:47104
	ds_read_b64_tr_b16 v[12:13], v218 offset:48128
	v_add_f32_e32 v82, v92, v90
	v_add_f32_e32 v83, v93, v91
	v_fma_f32 v2, v96, v5, v4
	s_waitcnt lgkmcnt(2)
	v_mfma_f32_32x32x16_bf16 v[66:81], v[14:17], v[6:9], v[66:81]
	ds_read_b64_tr_b16 v[14:15], v217 offset:45120
	ds_read_b64_tr_b16 v[16:17], v217 offset:46144
	v_add_f32_e64 v87, v82, v83
	v_fmac_f32_e32 v4, v97, v5
	ds_read_b64_tr_b16 v[82:83], v217 offset:47168
	ds_read_b64_tr_b16 v[84:85], v217 offset:48192
	v_exp_f32_e32 v2, v2
	v_exp_f32_e32 v86, v4
	v_cvt_pk_bf16_f32 v4, v249, v88
	s_waitcnt lgkmcnt(2)
	v_mfma_f32_32x32x16_bf16 v[50:65], v[14:17], v[6:9], v[50:65]
	v_cvt_pk_bf16_f32 v5, v108, v102
	v_cvt_pk_bf16_f32 v6, v94, v90
	v_cvt_pk_bf16_f32 v7, v2, v86
	v_add_f32_e32 v107, v109, v2
	v_add_f32_e64 v8, v106, v86
	v_add_f32_e64 v9, v107, v87
	v_add_f32_e32 v2, v8, v9
	v_mfma_f32_32x32x16_bf16 v[66:81], v[10:13], v[4:7], v[66:81]
	v_add_f32_e32 v214, v214, v2
	s_waitcnt lgkmcnt(0)
	v_mfma_f32_32x32x16_bf16 v[50:65], v[82:85], v[4:7], v[50:65]
	s_add_i32 s52, s52, -3
	s_andn2_b64 vcc, exec, s[6:7]
	s_add_i32 s53, s53, 0xc000
	s_cbranch_vccz .LBB0_712

; #define LAS __attribute__((address_space(3)))
; #define MFMA32(a, b, c) __builtin_amdgcn_mfma_f32_32x32x16_bf16((a), (b), (c), 0, 0, 0)
; DI float fexp2(float x) { return __builtin_amdgcn_exp2f(x); }
; DI s16x4 vtr(const LAS unsigned char* p) { return __builtin_bit_cast(s16x4, __builtin_amdgcn_ds_read_tr16_b64_v4i16((LAS v4i16_t*)p)); }
; DI void flash_pv(FState& st, f32x16& p0, f32x16& p1, bool rowon, const LAS unsigned char* vb, int lane) {
;     ...
;     const float cl = rowon ? SM_C : 0.0f;
;     const float bl = rowon ? ((st.m == NINF) ? 0.0f : -st.m * SM_C) : NINF;
;     float sum = 0.f;
; #pragma unroll
;     for (int r = 0; r < 16; ++r) { p0[r] = fexp2(__builtin_fmaf(p0[r], cl, bl)); p1[r] = fexp2(__builtin_fmaf(p1[r], cl, bl)); sum += p0[r] + p1[r]; }
;     st.l += sum;
;     const int h = lane >> 5;
;     const int vx = (((lane & 15) >> 3) & 1) * 64;
;     const LAS unsigned char* vp = vb + (4 * h + ((lane & 15) >> 2)) * 128 + ((lane >> 4) & 1) * 32 + (lane & 3) * 8;
; #pragma unroll
;     for (int sub = 0; sub < 2; ++sub)
; #pragma unroll
;         for (int s2 = 0; s2 < 2; ++s2) {
;             const bf16x8 pf = pack8h(sub ? p1 : p0, s2);
;             const LAS unsigned char* vq = vp + (32 * sub + 16 * s2) * 128;
;             { const s16x4 lo = vtr(vq + vx), hi = vtr(vq + 1024 + vx); const bf16x8 vf = {lo[0], lo[1], lo[2], lo[3], hi[0], hi[1], hi[2], hi[3]}; st.o0 = MFMA32(vf, pf, st.o0); }
;             { const s16x4 lo = vtr(vq + (64 - vx)), hi = vtr(vq + 1024 + (64 - vx)); const bf16x8 vf = {lo[0], lo[1], lo[2], lo[3], hi[0], hi[1], hi[2], hi[3]}; st.o1 = MFMA32(vf, pf, st.o1); }
.Lnq_759:
	s_or_b64 exec, exec, s[4:5]
	v_fma_f32 v2, v130, v5, v4
	v_exp_f32_e32 v12, v2
	v_fma_f32 v2, v114, v5, v4
	v_exp_f32_e32 v246, v2
	s_waitcnt lgkmcnt(3)
	v_mfma_f32_32x32x16_bf16 v[98:113], v[226:229], v[154:157], v[98:113]
	v_fma_f32 v2, v131, v5, v4
	v_exp_f32_e32 v6, v2
	v_fma_f32 v2, v115, v5, v4
	v_exp_f32_e32 v2, v2
	v_add_f32_e32 v7, v12, v246
	s_add_i32 s77, s74, 1
	s_cmp_ge_u32 s77, s51
	v_add_f32_e32 v8, v6, v2
	v_add_f32_e32 v9, v7, v3
	v_fma_f32 v7, v132, v5, v4
	v_add_f32_e32 v131, v8, v9
	s_waitcnt lgkmcnt(2)
	v_mfma_f32_32x32x16_bf16 v[82:97], v[230:233], v[154:157], v[82:97]
	v_fma_f32 v8, v116, v5, v4
	v_exp_f32_e32 v7, v7
	v_exp_f32_e32 v247, v8
	v_fma_f32 v8, v133, v5, v4
	v_fma_f32 v9, v117, v5, v4
	v_exp_f32_e32 v8, v8
	v_exp_f32_e32 v130, v9
	v_add_f32_e32 v9, v7, v247
	v_cvt_pk_bf16_f32 v6, v12, v6
	v_cvt_pk_bf16_f32 v7, v7, v8
	s_waitcnt lgkmcnt(1)
	v_mfma_f32_32x32x16_bf16 v[98:113], v[234:237], v[158:161], v[98:113]
	v_add_f32_e32 v10, v8, v130
	v_add_f32_e32 v11, v9, v131
	v_fma_f32 v9, v134, v5, v4
	v_add_f32_e32 v133, v10, v11
	v_fma_f32 v10, v118, v5, v4
	v_exp_f32_e32 v131, v10
	v_fma_f32 v10, v135, v5, v4
	v_exp_f32_e32 v9, v9
	v_exp_f32_e32 v14, v10
	v_fma_f32 v10, v119, v5, v4
	v_exp_f32_e32 v132, v10
	s_waitcnt lgkmcnt(0)
	v_mfma_f32_32x32x16_bf16 v[82:97], v[238:241], v[158:161], v[82:97]
	v_add_f32_e32 v15, v9, v131
	v_cvt_pk_bf16_f32 v8, v9, v14
	v_add_f32_e32 v10, v14, v132
	v_add_f32_e32 v11, v15, v133
	s_nop 0
	v_add_f32_e32 v119, v10, v11
	v_fma_f32 v10, v136, v5, v4
	v_exp_f32_e32 v15, v10
	v_fma_f32 v10, v120, v5, v4
	v_exp_f32_e32 v133, v10
	v_fma_f32 v10, v137, v5, v4
	v_exp_f32_e32 v16, v10
	v_fma_f32 v10, v121, v5, v4
	v_exp_f32_e32 v118, v10
	v_add_f32_e32 v17, v15, v133
	v_cvt_pk_bf16_f32 v9, v15, v16
	v_add_f32_e32 v10, v16, v118
	v_add_f32_e32 v11, v17, v119
	s_nop 0
	v_add_f32_e32 v121, v10, v11
	v_fma_f32 v10, v138, v5, v4
	v_exp_f32_e32 v119, v10
	v_fma_f32 v10, v122, v5, v4
	v_exp_f32_e32 v248, v10
	v_fma_f32 v10, v139, v5, v4
	v_exp_f32_e32 v122, v10
	v_fma_f32 v10, v123, v5, v4
	v_exp_f32_e32 v120, v10
	v_fma_f32 v10, v140, v5, v4
	v_exp_f32_e32 v139, v10
	v_fma_f32 v10, v124, v5, v4
	v_add_f32_e32 v123, v119, v248
	v_exp_f32_e32 v140, v10
	v_add_f32_e32 v10, v122, v120
	v_add_f32_e32 v11, v123, v121
	v_fma_f32 v123, v144, v5, v4
	v_add_f32_e32 v135, v10, v11
	v_fma_f32 v10, v141, v5, v4
	v_exp_f32_e32 v136, v10
	v_fma_f32 v10, v125, v5, v4
	v_exp_f32_e32 v134, v10
	ds_read_b64_tr_b16 v[10:11], v218 offset:8192
	ds_read_b64_tr_b16 v[12:13], v218 offset:9216
	ds_read_b64_tr_b16 v[14:15], v217 offset:8256
	ds_read_b64_tr_b16 v[16:17], v217 offset:9280
	ds_read_b64_tr_b16 v[114:115], v218 offset:10240
	ds_read_b64_tr_b16 v[116:117], v218 offset:11264
	s_waitcnt lgkmcnt(4)
	v_mfma_f32_32x32x16_bf16 v[66:81], v[10:13], v[6:9], v[66:81]
	v_fma_f32 v10, v142, v5, v4
	v_exp_f32_e32 v121, v10
	v_fma_f32 v10, v143, v5, v4
	v_exp_f32_e32 v124, v10
	v_exp_f32_e32 v141, v123
	v_add_f32_e32 v137, v139, v140
	ds_read_b64_tr_b16 v[10:11], v217 offset:10304
	ds_read_b64_tr_b16 v[12:13], v217 offset:11328
	s_waitcnt lgkmcnt(4)
	v_mfma_f32_32x32x16_bf16 v[50:65], v[14:17], v[6:9], v[50:65]
	v_fma_f32 v6, v145, v5, v4
	v_exp_f32_e32 v138, v6
	v_cvt_pk_bf16_f32 v6, v119, v122
	v_cvt_pk_bf16_f32 v7, v139, v136
	v_cvt_pk_bf16_f32 v8, v121, v124
	v_cvt_pk_bf16_f32 v9, v141, v138
	v_add_f32_e32 v14, v136, v134
	v_add_f32_e32 v15, v137, v135
	s_waitcnt lgkmcnt(2)
	v_mfma_f32_32x32x16_bf16 v[66:81], v[114:117], v[6:9], v[66:81]
	v_add_f32_e64 v123, v14, v15
	v_fma_f32 v14, v126, v5, v4
	v_exp_f32_e32 v126, v14
	ds_read_b64_tr_b16 v[14:15], v218 offset:12288
	ds_read_b64_tr_b16 v[16:17], v218 offset:13312
	v_fma_f32 v114, v127, v5, v4
	v_exp_f32_e32 v122, v114
	v_add_f32_e32 v125, v121, v126
	s_waitcnt lgkmcnt(2)
	v_mfma_f32_32x32x16_bf16 v[50:65], v[10:13], v[6:9], v[50:65]
	v_cvt_pk_bf16_f32 v6, v246, v2
	v_cvt_pk_bf16_f32 v7, v247, v130
	v_cvt_pk_bf16_f32 v8, v131, v132
	v_cvt_pk_bf16_f32 v9, v133, v118
	ds_read_b64_tr_b16 v[10:11], v218 offset:14336
	ds_read_b64_tr_b16 v[12:13], v218 offset:15360
	v_add_f32_e32 v114, v124, v122
	v_add_f32_e32 v115, v125, v123
	v_fma_f32 v2, v128, v5, v4
	s_waitcnt lgkmcnt(2)
	v_mfma_f32_32x32x16_bf16 v[66:81], v[14:17], v[6:9], v[66:81]
	ds_read_b64_tr_b16 v[14:15], v217 offset:12352
	ds_read_b64_tr_b16 v[16:17], v217 offset:13376
	v_add_f32_e64 v119, v114, v115
	v_fmac_f32_e32 v4, v129, v5
	ds_read_b64_tr_b16 v[114:115], v217 offset:14400
	ds_read_b64_tr_b16 v[116:117], v217 offset:15424
	v_exp_f32_e32 v2, v2
	v_exp_f32_e32 v118, v4
	v_cvt_pk_bf16_f32 v4, v248, v120
	s_waitcnt lgkmcnt(2)
	v_mfma_f32_32x32x16_bf16 v[50:65], v[14:17], v[6:9], v[50:65]
	v_cvt_pk_bf16_f32 v5, v140, v134
	v_cvt_pk_bf16_f32 v6, v126, v122
	v_cvt_pk_bf16_f32 v7, v2, v118
	v_add_f32_e32 v139, v141, v2
	v_add_f32_e64 v8, v138, v118
	v_add_f32_e64 v9, v139, v119
	v_add_f32_e32 v2, v8, v9
	v_mfma_f32_32x32x16_bf16 v[66:81], v[10:13], v[4:7], v[66:81]
	v_add_f32_e32 v214, v214, v2
	s_waitcnt lgkmcnt(0)
	v_mfma_f32_32x32x16_bf16 v[50:65], v[114:117], v[4:7], v[50:65]
	s_cbranch_scc1 .Lnq_780
	s_movk_i32 s76, 0x4000
	s_add_i32 s4, s74, 5
	s_cmp_ge_u32 s4, s51
	s_waitcnt vmcnt(1)
	ds_write_b128 v205, v[182:185] offset:32768
	s_waitcnt vmcnt(0)
	ds_write_b128 v212, v[178:181] offset:40960
	s_waitcnt lgkmcnt(0)
	s_barrier
	s_cbranch_scc1 .Lnq_762
	s_cmp_gt_u32 s4, s69
	s_cselect_b64 s[8:9], -1, 0
	s_mov_b32 s5, s52
	s_and_b64 s[8:9], s[8:9], exec
	s_cselect_b32 s4, s5, s4
	s_cselect_b32 s16, 0x1000, s65
	s_cselect_b32 s8, s64, 0x500
	s_lshl_b32 s4, s4, 6
	s_mov_b32 s9, s17
	v_mad_i64_i32 v[4:5], s[4:5], s4, v199, v[192:193]
	v_lshl_add_u64 v[6:7], v[4:5], 0, s[8:9]
	v_lshl_add_u64 v[4:5], v[4:5], 0, s[16:17]
	global_load_dwordx4 v[182:185], v[6:7], off
	global_load_dwordx4 v[178:181], v[4:5], off

; #define LAS __attribute__((address_space(3)))
; #define MFMA32(a, b, c) __builtin_amdgcn_mfma_f32_32x32x16_bf16((a), (b), (c), 0, 0, 0)
; DI float fexp2(float x) { return __builtin_amdgcn_exp2f(x); }
; DI s16x4 vtr(const LAS unsigned char* p) { return __builtin_bit_cast(s16x4, __builtin_amdgcn_ds_read_tr16_b64_v4i16((LAS v4i16_t*)p)); }
; DI void flash_pv(FState& st, f32x16& p0, f32x16& p1, bool rowon, const LAS unsigned char* vb, int lane) {
;     ...
;     const float cl = rowon ? SM_C : 0.0f;
;     const float bl = rowon ? ((st.m == NINF) ? 0.0f : -st.m * SM_C) : NINF;
;     float sum = 0.f;
; #pragma unroll
;     for (int r = 0; r < 16; ++r) { p0[r] = fexp2(__builtin_fmaf(p0[r], cl, bl)); p1[r] = fexp2(__builtin_fmaf(p1[r], cl, bl)); sum += p0[r] + p1[r]; }
;     st.l += sum;
;     const int h = lane >> 5;
;     const int vx = (((lane & 15) >> 3) & 1) * 64;
;     const LAS unsigned char* vp = vb + (4 * h + ((lane & 15) >> 2)) * 128 + ((lane >> 4) & 1) * 32 + (lane & 3) * 8;
; #pragma unroll
;     for (int sub = 0; sub < 2; ++sub)
; #pragma unroll
;         for (int s2 = 0; s2 < 2; ++s2) {
;             const bf16x8 pf = pack8h(sub ? p1 : p0, s2);
;             const LAS unsigned char* vq = vp + (32 * sub + 16 * s2) * 128;
;             { const s16x4 lo = vtr(vq + vx), hi = vtr(vq + 1024 + vx); const bf16x8 vf = {lo[0], lo[1], lo[2], lo[3], hi[0], hi[1], hi[2], hi[3]}; st.o0 = MFMA32(vf, pf, st.o0); }
;             { const s16x4 lo = vtr(vq + (64 - vx)), hi = vtr(vq + 1024 + (64 - vx)); const bf16x8 vf = {lo[0], lo[1], lo[2], lo[3], hi[0], hi[1], hi[2], hi[3]}; st.o1 = MFMA32(vf, pf, st.o1); }
.Lnq_778:
	s_or_b64 exec, exec, s[4:5]
	v_fma_f32 v2, v98, v5, v4
	v_exp_f32_e32 v12, v2
	v_fma_f32 v2, v82, v5, v4
	v_exp_f32_e32 v246, v2
	s_waitcnt lgkmcnt(3)
	v_mfma_f32_32x32x16_bf16 v[130:145], v[226:229], v[154:157], v[130:145]
	v_fma_f32 v2, v99, v5, v4
	v_exp_f32_e32 v6, v2
	v_fma_f32 v2, v83, v5, v4
	v_exp_f32_e32 v2, v2
	v_add_f32_e32 v7, v12, v246
	v_add_f32_e32 v8, v6, v2
	v_add_f32_e32 v9, v7, v3
	s_nop 0
	v_add_f32_e32 v99, v8, v9
	v_fma_f32 v7, v100, v5, v4
	v_fma_f32 v8, v84, v5, v4
	s_waitcnt lgkmcnt(2)
	v_mfma_f32_32x32x16_bf16 v[114:129], v[230:233], v[154:157], v[114:129]
	v_exp_f32_e32 v7, v7
	v_exp_f32_e32 v247, v8
	v_fma_f32 v8, v101, v5, v4
	v_fma_f32 v9, v85, v5, v4
	v_exp_f32_e32 v8, v8
	v_exp_f32_e32 v98, v9
	v_add_f32_e32 v9, v7, v247
	v_cvt_pk_bf16_f32 v6, v12, v6
	v_cvt_pk_bf16_f32 v7, v7, v8
	v_add_f32_e32 v10, v8, v98
	v_add_f32_e32 v11, v9, v99
	s_waitcnt lgkmcnt(1)
	v_mfma_f32_32x32x16_bf16 v[130:145], v[234:237], v[158:161], v[130:145]
	v_fma_f32 v9, v102, v5, v4
	v_add_f32_e32 v101, v10, v11
	v_fma_f32 v10, v86, v5, v4
	v_exp_f32_e32 v99, v10
	v_fma_f32 v10, v103, v5, v4
	v_exp_f32_e32 v9, v9
	v_exp_f32_e32 v14, v10
	v_fma_f32 v10, v87, v5, v4
	v_exp_f32_e32 v100, v10
	v_add_f32_e32 v15, v9, v99
	s_waitcnt lgkmcnt(0)
	v_mfma_f32_32x32x16_bf16 v[114:129], v[238:241], v[158:161], v[114:129]
	v_cvt_pk_bf16_f32 v8, v9, v14
	v_add_f32_e32 v10, v14, v100
	v_add_f32_e32 v11, v15, v101
	s_nop 0
	v_add_f32_e32 v87, v10, v11
	v_fma_f32 v10, v104, v5, v4
	v_exp_f32_e32 v15, v10
	v_fma_f32 v10, v88, v5, v4
	v_exp_f32_e32 v101, v10
	v_fma_f32 v10, v105, v5, v4
	v_exp_f32_e32 v16, v10
	v_fma_f32 v10, v89, v5, v4
	v_exp_f32_e32 v86, v10
	v_add_f32_e32 v17, v15, v101
	v_cvt_pk_bf16_f32 v9, v15, v16
	v_add_f32_e32 v10, v16, v86
	v_add_f32_e32 v11, v17, v87
	s_nop 0
	v_add_f32_e32 v89, v10, v11
	v_fma_f32 v10, v106, v5, v4
	v_exp_f32_e32 v87, v10
	v_fma_f32 v10, v90, v5, v4
	v_exp_f32_e32 v248, v10
	v_fma_f32 v10, v107, v5, v4
	v_exp_f32_e32 v90, v10
	v_fma_f32 v10, v91, v5, v4
	v_exp_f32_e32 v88, v10
	v_fma_f32 v10, v108, v5, v4
	v_exp_f32_e32 v107, v10
	v_fma_f32 v10, v92, v5, v4
	v_add_f32_e32 v91, v87, v248
	v_exp_f32_e32 v108, v10
	v_add_f32_e32 v10, v90, v88
	v_add_f32_e32 v11, v91, v89
	v_fma_f32 v91, v112, v5, v4
	v_add_f32_e32 v103, v10, v11
	v_fma_f32 v10, v109, v5, v4
	v_exp_f32_e32 v104, v10
	v_fma_f32 v10, v93, v5, v4
	v_exp_f32_e32 v102, v10
	ds_read_b64_tr_b16 v[10:11], v218 offset:24576
	ds_read_b64_tr_b16 v[12:13], v218 offset:25600
	ds_read_b64_tr_b16 v[14:15], v217 offset:24640
	ds_read_b64_tr_b16 v[16:17], v217 offset:25664
	ds_read_b64_tr_b16 v[82:83], v218 offset:26624
	ds_read_b64_tr_b16 v[84:85], v218 offset:27648
	s_waitcnt lgkmcnt(4)
	v_mfma_f32_32x32x16_bf16 v[66:81], v[10:13], v[6:9], v[66:81]
	v_fma_f32 v10, v110, v5, v4
	v_exp_f32_e32 v93, v10
	v_fma_f32 v10, v111, v5, v4
	v_exp_f32_e32 v92, v10
	v_exp_f32_e32 v110, v91
	v_add_f32_e32 v105, v107, v108
	ds_read_b64_tr_b16 v[10:11], v217 offset:26688
	ds_read_b64_tr_b16 v[12:13], v217 offset:27712
	s_waitcnt lgkmcnt(4)
	v_mfma_f32_32x32x16_bf16 v[50:65], v[14:17], v[6:9], v[50:65]
	v_fma_f32 v6, v113, v5, v4
	v_exp_f32_e32 v106, v6
	v_cvt_pk_bf16_f32 v6, v87, v90
	v_cvt_pk_bf16_f32 v7, v107, v104
	v_cvt_pk_bf16_f32 v8, v93, v92
	v_cvt_pk_bf16_f32 v9, v110, v106
	v_add_f32_e32 v14, v104, v102
	v_add_f32_e32 v15, v105, v103
	s_waitcnt lgkmcnt(2)
	v_mfma_f32_32x32x16_bf16 v[66:81], v[82:85], v[6:9], v[66:81]
	v_add_f32_e64 v91, v14, v15
	v_fma_f32 v14, v94, v5, v4
	v_exp_f32_e32 v94, v14
	ds_read_b64_tr_b16 v[14:15], v218 offset:28672
	ds_read_b64_tr_b16 v[16:17], v218 offset:29696
	v_fma_f32 v82, v95, v5, v4
	v_exp_f32_e32 v90, v82
	v_add_f32_e32 v93, v93, v94
	s_waitcnt lgkmcnt(2)
	v_mfma_f32_32x32x16_bf16 v[50:65], v[10:13], v[6:9], v[50:65]
	v_cvt_pk_bf16_f32 v6, v246, v2
	v_cvt_pk_bf16_f32 v7, v247, v98
	v_cvt_pk_bf16_f32 v8, v99, v100
	v_cvt_pk_bf16_f32 v9, v101, v86
	ds_read_b64_tr_b16 v[10:11], v218 offset:30720
	ds_read_b64_tr_b16 v[12:13], v218 offset:31744
	v_add_f32_e32 v82, v92, v90
	v_add_f32_e32 v83, v93, v91
	v_fma_f32 v2, v96, v5, v4
	s_waitcnt lgkmcnt(2)
	v_mfma_f32_32x32x16_bf16 v[66:81], v[14:17], v[6:9], v[66:81]
	ds_read_b64_tr_b16 v[14:15], v217 offset:28736
	ds_read_b64_tr_b16 v[16:17], v217 offset:29760
	v_add_f32_e64 v87, v82, v83
	v_fmac_f32_e32 v4, v97, v5
	ds_read_b64_tr_b16 v[82:83], v217 offset:30784
	ds_read_b64_tr_b16 v[84:85], v217 offset:31808
	v_exp_f32_e32 v2, v2
	v_exp_f32_e32 v86, v4
	v_cvt_pk_bf16_f32 v4, v248, v88
	s_waitcnt lgkmcnt(2)
	v_mfma_f32_32x32x16_bf16 v[50:65], v[14:17], v[6:9], v[50:65]
	v_cvt_pk_bf16_f32 v5, v108, v102
	v_cvt_pk_bf16_f32 v6, v94, v90
	v_cvt_pk_bf16_f32 v7, v2, v86
	v_add_f32_e32 v107, v110, v2
	v_add_f32_e64 v8, v106, v86
	v_add_f32_e64 v9, v107, v87
	v_add_f32_e32 v2, v8, v9
	v_mfma_f32_32x32x16_bf16 v[66:81], v[10:13], v[4:7], v[66:81]
	v_add_f32_e32 v214, v214, v2
	s_waitcnt lgkmcnt(0)
	v_mfma_f32_32x32x16_bf16 v[50:65], v[82:85], v[4:7], v[50:65]
	s_add_i32 s76, s74, 2
	s_cmp_ge_u32 s76, s51
	s_cbranch_scc0 .Lnq_781

; #define LAS __attribute__((address_space(3)))
; #define MFMA32(a, b, c) __builtin_amdgcn_mfma_f32_32x32x16_bf16((a), (b), (c), 0, 0, 0)
; DI float fexp2(float x) { return __builtin_amdgcn_exp2f(x); }
; DI s16x4 vtr(const LAS unsigned char* p) { return __builtin_bit_cast(s16x4, __builtin_amdgcn_ds_read_tr16_b64_v4i16((LAS v4i16_t*)p)); }
; DI void flash_pv(FState& st, f32x16& p0, f32x16& p1, bool rowon, const LAS unsigned char* vb, int lane) {
;     ...
;     const float cl = rowon ? SM_C : 0.0f;
;     const float bl = rowon ? ((st.m == NINF) ? 0.0f : -st.m * SM_C) : NINF;
;     float sum = 0.f;
; #pragma unroll
;     for (int r = 0; r < 16; ++r) { p0[r] = fexp2(__builtin_fmaf(p0[r], cl, bl)); p1[r] = fexp2(__builtin_fmaf(p1[r], cl, bl)); sum += p0[r] + p1[r]; }
;     st.l += sum;
;     const int h = lane >> 5;
;     const int vx = (((lane & 15) >> 3) & 1) * 64;
;     const LAS unsigned char* vp = vb + (4 * h + ((lane & 15) >> 2)) * 128 + ((lane >> 4) & 1) * 32 + (lane & 3) * 8;
; #pragma unroll
;     for (int sub = 0; sub < 2; ++sub)
; #pragma unroll
;         for (int s2 = 0; s2 < 2; ++s2) {
;             const bf16x8 pf = pack8h(sub ? p1 : p0, s2);
;             const LAS unsigned char* vq = vp + (32 * sub + 16 * s2) * 128;
;             { const s16x4 lo = vtr(vq + vx), hi = vtr(vq + 1024 + vx); const bf16x8 vf = {lo[0], lo[1], lo[2], lo[3], hi[0], hi[1], hi[2], hi[3]}; st.o0 = MFMA32(vf, pf, st.o0); }
;             { const s16x4 lo = vtr(vq + (64 - vx)), hi = vtr(vq + 1024 + (64 - vx)); const bf16x8 vf = {lo[0], lo[1], lo[2], lo[3], hi[0], hi[1], hi[2], hi[3]}; st.o1 = MFMA32(vf, pf, st.o1); }
.Lnq_799:
	s_or_b64 exec, exec, s[4:5]
	v_fma_f32 v2, v130, v5, v4
	v_exp_f32_e32 v246, v2
	v_fma_f32 v2, v114, v5, v4
	v_exp_f32_e32 v247, v2
	s_waitcnt lgkmcnt(3)
	v_mfma_f32_32x32x16_bf16 v[98:113], v[226:229], v[154:157], v[98:113]
	v_fma_f32 v2, v131, v5, v4
	v_exp_f32_e32 v10, v2
	v_fma_f32 v2, v115, v5, v4
	v_exp_f32_e32 v2, v2
	v_add_f32_e32 v11, v246, v247
	v_add_f32_e32 v6, v10, v2
	v_add_f32_e32 v7, v11, v3
	s_nop 0
	v_add_f32_e32 v131, v6, v7
	v_fma_f32 v6, v132, v5, v4
	v_exp_f32_e32 v11, v6
	s_waitcnt lgkmcnt(2)
	v_mfma_f32_32x32x16_bf16 v[82:97], v[230:233], v[154:157], v[82:97]
	v_fma_f32 v6, v116, v5, v4
	v_exp_f32_e32 v248, v6
	v_fma_f32 v6, v133, v5, v4
	v_exp_f32_e32 v12, v6
	v_fma_f32 v6, v117, v5, v4
	v_exp_f32_e32 v130, v6
	v_add_f32_e32 v13, v11, v248
	v_cvt_pk_bf16_f32 v10, v246, v10
	v_cvt_pk_bf16_f32 v11, v11, v12
	v_add_f32_e32 v6, v12, v130
	v_add_f32_e32 v7, v13, v131
	s_waitcnt lgkmcnt(1)
	v_mfma_f32_32x32x16_bf16 v[98:113], v[234:237], v[158:161], v[98:113]
	s_nop 0
	v_add_f32_e32 v133, v6, v7
	v_fma_f32 v6, v134, v5, v4
	v_exp_f32_e32 v13, v6
	v_fma_f32 v6, v118, v5, v4
	v_exp_f32_e32 v131, v6
	v_fma_f32 v6, v135, v5, v4
	v_exp_f32_e32 v14, v6
	v_fma_f32 v6, v119, v5, v4
	v_exp_f32_e32 v132, v6
	s_waitcnt lgkmcnt(0)
	v_mfma_f32_32x32x16_bf16 v[82:97], v[238:241], v[158:161], v[82:97]
	v_add_f32_e32 v15, v13, v131
	v_cvt_pk_bf16_f32 v12, v13, v14
	v_add_f32_e32 v6, v14, v132
	v_add_f32_e32 v7, v15, v133
	s_nop 0
	v_add_f32_e32 v119, v6, v7
	v_fma_f32 v6, v136, v5, v4
	v_exp_f32_e32 v15, v6
	v_fma_f32 v6, v120, v5, v4
	v_exp_f32_e32 v133, v6
	v_fma_f32 v6, v137, v5, v4
	v_exp_f32_e32 v16, v6
	v_fma_f32 v6, v121, v5, v4
	v_exp_f32_e32 v118, v6
	v_add_f32_e32 v17, v15, v133
	v_cvt_pk_bf16_f32 v13, v15, v16
	v_add_f32_e32 v6, v16, v118
	v_add_f32_e32 v7, v17, v119
	s_nop 0
	v_add_f32_e32 v121, v6, v7
	v_fma_f32 v6, v138, v5, v4
	v_exp_f32_e32 v119, v6
	v_fma_f32 v6, v122, v5, v4
	v_exp_f32_e32 v249, v6
	v_fma_f32 v6, v139, v5, v4
	v_exp_f32_e32 v122, v6
	v_fma_f32 v6, v123, v5, v4
	v_exp_f32_e32 v120, v6
	v_fma_f32 v6, v140, v5, v4
	v_exp_f32_e32 v139, v6
	v_fma_f32 v6, v124, v5, v4
	v_add_f32_e32 v123, v119, v249
	v_exp_f32_e32 v140, v6
	v_add_f32_e32 v6, v122, v120
	v_add_f32_e32 v7, v123, v121
	v_fma_f32 v123, v144, v5, v4
	v_add_f32_e32 v135, v6, v7
	v_fma_f32 v6, v141, v5, v4
	v_exp_f32_e32 v136, v6
	v_fma_f32 v6, v125, v5, v4
	v_exp_f32_e32 v134, v6
	ds_read_b64_tr_b16 v[6:7], v218 offset:40960
	ds_read_b64_tr_b16 v[8:9], v218 offset:41984
	ds_read_b64_tr_b16 v[14:15], v217 offset:41024
	ds_read_b64_tr_b16 v[16:17], v217 offset:42048
	ds_read_b64_tr_b16 v[114:115], v218 offset:43008
	ds_read_b64_tr_b16 v[116:117], v218 offset:44032
	s_waitcnt lgkmcnt(4)
	v_mfma_f32_32x32x16_bf16 v[66:81], v[6:9], v[10:13], v[66:81]
	v_fma_f32 v6, v142, v5, v4
	v_exp_f32_e32 v121, v6
	v_fma_f32 v6, v143, v5, v4
	v_exp_f32_e32 v124, v6
	v_exp_f32_e32 v141, v123
	v_add_f32_e32 v137, v139, v140
	ds_read_b64_tr_b16 v[6:7], v217 offset:43072
	ds_read_b64_tr_b16 v[8:9], v217 offset:44096
	s_waitcnt lgkmcnt(4)
	v_mfma_f32_32x32x16_bf16 v[50:65], v[14:17], v[10:13], v[50:65]
	v_fma_f32 v10, v145, v5, v4
	v_exp_f32_e32 v138, v10
	v_cvt_pk_bf16_f32 v10, v119, v122
	v_cvt_pk_bf16_f32 v11, v139, v136
	v_cvt_pk_bf16_f32 v12, v121, v124
	v_cvt_pk_bf16_f32 v13, v141, v138
	v_add_f32_e32 v14, v136, v134
	v_add_f32_e32 v15, v137, v135
	s_waitcnt lgkmcnt(2)
	v_mfma_f32_32x32x16_bf16 v[66:81], v[114:117], v[10:13], v[66:81]
	v_add_f32_e64 v123, v14, v15
	v_fma_f32 v14, v126, v5, v4
	v_exp_f32_e32 v126, v14
	ds_read_b64_tr_b16 v[14:15], v218 offset:45056
	ds_read_b64_tr_b16 v[16:17], v218 offset:46080
	v_fma_f32 v114, v127, v5, v4
	v_exp_f32_e32 v122, v114
	v_add_f32_e32 v125, v121, v126
	s_waitcnt lgkmcnt(2)
	v_mfma_f32_32x32x16_bf16 v[50:65], v[6:9], v[10:13], v[50:65]
	v_cvt_pk_bf16_f32 v6, v247, v2
	v_cvt_pk_bf16_f32 v7, v248, v130
	v_cvt_pk_bf16_f32 v8, v131, v132
	v_cvt_pk_bf16_f32 v9, v133, v118
	ds_read_b64_tr_b16 v[10:11], v218 offset:47104
	ds_read_b64_tr_b16 v[12:13], v218 offset:48128
	v_add_f32_e32 v114, v124, v122
	v_add_f32_e32 v115, v125, v123
	v_fma_f32 v2, v128, v5, v4
	s_waitcnt lgkmcnt(2)
	v_mfma_f32_32x32x16_bf16 v[66:81], v[14:17], v[6:9], v[66:81]
	ds_read_b64_tr_b16 v[14:15], v217 offset:45120
	ds_read_b64_tr_b16 v[16:17], v217 offset:46144
	v_add_f32_e64 v119, v114, v115
	v_fmac_f32_e32 v4, v129, v5
	ds_read_b64_tr_b16 v[114:115], v217 offset:47168
	ds_read_b64_tr_b16 v[116:117], v217 offset:48192
	v_exp_f32_e32 v2, v2
	v_exp_f32_e32 v118, v4
	v_cvt_pk_bf16_f32 v4, v249, v120
	s_waitcnt lgkmcnt(2)
	v_mfma_f32_32x32x16_bf16 v[50:65], v[14:17], v[6:9], v[50:65]
	v_cvt_pk_bf16_f32 v5, v140, v134
	v_cvt_pk_bf16_f32 v6, v126, v122
	v_cvt_pk_bf16_f32 v7, v2, v118
	v_add_f32_e32 v139, v141, v2
	v_add_f32_e64 v8, v138, v118
	v_add_f32_e64 v9, v139, v119
	v_add_f32_e32 v2, v8, v9
	v_mfma_f32_32x32x16_bf16 v[66:81], v[10:13], v[4:7], v[66:81]
	v_add_f32_e32 v214, v214, v2
	s_waitcnt lgkmcnt(0)
	v_mfma_f32_32x32x16_bf16 v[50:65], v[114:117], v[4:7], v[50:65]
	s_add_i32 s52, s52, -3
	s_andn2_b64 vcc, exec, s[6:7]
	s_add_i32 s53, s53, 0xc000
	s_cbranch_vccz .LBB0_712
